# POST gMLP loop: first gate-value load issued with the weight-fragment loads so its latency hides behind the MFMA chain
# baseline (speedup 1.0000x reference)
; __device__ __forceinline__ unsigned short f2bf(float f) { return (unsigned short)(pk2(f, 0.f) & 0xffffu); }
; __device__ __forceinline__ float bf2f(unsigned short h) { return __uint_as_float(((unsigned)h) << 16); }
; __device__ __forceinline__ float gelu_t(float x) { const float t = x * (-2.3022082f + -0.10294324f * x * x); return x * __builtin_amdgcn_rcpf(1.0f + __builtin_amdgcn_exp2f(t)); }
; __device__ __forceinline__ void post_phase(const Params& p, int l, LAS unsigned char* lds, int tid) {
;     ...
;                 for (int pb = 0; pb < 4; ++pb) {
;                     unsigned short uu[16];
; #pragma unroll
;                     for (int e = 0; e < 16; ++e) uu[e] = px[(size_t)(pb * 32 + (e & 3) + 8 * (e >> 2) + 4 * hi) * NIN + 1280 + col];
;                     f32x16 acc;
; #pragma unroll
;                     for (int e = 0; e < 16; ++e) acc[e] = 0.f;
; #pragma unroll
;                     for (int s = 0; s < 8; ++s) {
;                         const bf16x8 a = *(const bf16x8*)(wsb + (size_t)(pb * 32 + r32) * 128 + 16 * s + 8 * hi);
;                         acc = __builtin_amdgcn_mfma_f32_32x32x16_bf16(a, bfr[s], acc, 0, 0, 0);
;                     }
; #pragma unroll
;                     for (int e = 0; e < 16; ++e) {
;                         const int pp = pb * 32 + (e & 3) + 8 * (e >> 2) + 4 * hi;
;                         MIX[(size_t)(R0 + pp) * KOUT + 768 + col] = f2bf(gelu_t(bf2f(uu[e])) * (acc[e] + bs[pp]));
;                     }
.LBB0_358:
	v_lshl_add_u64 v[102:103], s[88:89], 0, v[100:101]
	global_load_dwordx4 v[0:3], v[102:103], off offset:-128
	global_load_dwordx4 v[136:139], v[102:103], off offset:-96
	global_load_dwordx4 v[160:163], v[102:103], off offset:-64
	global_load_dwordx4 v[164:167], v[102:103], off offset:-32
	global_load_dwordx4 v[168:171], v[102:103], off
	global_load_dwordx4 v[172:175], v[102:103], off offset:32
	global_load_dwordx4 v[176:179], v[102:103], off offset:64
	global_load_dwordx4 v[180:183], v[102:103], off offset:96
	v_lshl_add_u64 v[104:105], s[88:89], 0, v[90:91]
	s_brev_b32 s4, 48
	v_lshl_add_u64 v[150:151], s[88:89], 0, v[98:99]
	v_add_co_u32_e32 v210, vcc, s4, v104
	v_lshl_add_u64 v[100:101], v[100:101], 0, s[80:81]
	v_lshl_add_u64 v[98:99], v[98:99], 0, s[96:97]
	v_addc_co_u32_e32 v211, vcc, 0, v105, vcc
	global_load_ushort v89, v[210:211], off offset:2560
	s_waitcnt vmcnt(8) lgkmcnt(7)
	v_mfma_f32_32x32x16_bf16 v[0:15], v[0:3], v[16:19], 0
	s_waitcnt vmcnt(7) lgkmcnt(6)
	v_mfma_f32_32x32x16_bf16 v[0:15], v[136:139], v[20:23], v[0:15]
	s_waitcnt vmcnt(6) lgkmcnt(5)
	v_mfma_f32_32x32x16_bf16 v[0:15], v[160:163], v[24:27], v[0:15]
	s_waitcnt vmcnt(5) lgkmcnt(4)
	v_mfma_f32_32x32x16_bf16 v[0:15], v[164:167], v[28:31], v[0:15]
	s_waitcnt vmcnt(4) lgkmcnt(3)
	v_mfma_f32_32x32x16_bf16 v[0:15], v[168:171], v[32:35], v[0:15]
	s_waitcnt vmcnt(3) lgkmcnt(2)
	v_mfma_f32_32x32x16_bf16 v[0:15], v[172:175], v[36:39], v[0:15]
	s_waitcnt vmcnt(2) lgkmcnt(1)
	v_mfma_f32_32x32x16_bf16 v[0:15], v[176:179], v[40:43], v[0:15]
	v_add_co_u32_e32 v102, vcc, s4, v104
	s_mov_b32 s4, 0xc001000
	s_nop 0
	v_addc_co_u32_e32 v103, vcc, 0, v105, vcc
	v_add_co_u32_e32 v152, vcc, s22, v150
	s_waitcnt vmcnt(1) lgkmcnt(0)
	v_mfma_f32_32x32x16_bf16 v[0:15], v[180:183], v[44:47], v[0:15]
	v_addc_co_u32_e32 v153, vcc, 0, v151, vcc
	s_waitcnt vmcnt(0)
	v_lshlrev_b32_e32 v89, 16, v89
	v_mul_f32_e32 v102, 0x3dd2d3e8, v89
	v_fma_f32 v102, -v102, v89, s21
	v_mul_f32_e32 v102, v102, v89
	v_exp_f32_e32 v102, v102
	v_add_co_u32_e32 v136, vcc, s4, v104
	s_mov_b32 s4, 0xc002000
	v_add_f32_e32 v102, 1.0, v102
	v_rcp_f32_e32 v102, v102
	v_addc_co_u32_e32 v137, vcc, 0, v105, vcc
	v_mul_f32_e32 v89, v102, v89
	v_lshl_add_u64 v[102:103], v[86:87], 0, s[0:1]
	global_load_dwordx4 v[146:149], v[102:103], off
	s_waitcnt vmcnt(0)
	v_add_f32_e32 v0, v0, v146
	global_load_ushort v146, v[136:137], off offset:2048
	v_add_co_u32_e32 v136, vcc, s4, v104
	s_mov_b32 s4, 0xc003000
	s_nop 0
	v_addc_co_u32_e32 v137, vcc, 0, v105, vcc
	global_load_ushort v156, v[136:137], off offset:1536
	v_add_co_u32_e32 v136, vcc, s4, v104
	s_mov_b32 s4, 0xc007000
	s_nop 0
	v_addc_co_u32_e32 v137, vcc, 0, v105, vcc
	global_load_ushort v157, v[136:137], off offset:1024
	v_add_co_u32_e32 v136, vcc, s4, v104
	s_mov_b32 s4, 0xc008000
	s_nop 0
	v_addc_co_u32_e32 v137, vcc, 0, v105, vcc
	global_load_ushort v158, v[136:137], off offset:2560
	v_add_co_u32_e32 v136, vcc, s4, v104
	s_mov_b32 s4, 0xc009000
	s_nop 0
	v_addc_co_u32_e32 v137, vcc, 0, v105, vcc
	global_load_ushort v145, v[136:137], off offset:2048
	v_add_co_u32_e32 v136, vcc, s4, v104
	s_mov_b32 s4, 0xc00a000
	s_nop 0
	v_addc_co_u32_e32 v137, vcc, 0, v105, vcc
	global_load_ushort v143, v[136:137], off offset:1536
	v_add_co_u32_e32 v136, vcc, s4, v104
	s_mov_b32 s4, 0xc00e000
	s_nop 0
	v_addc_co_u32_e32 v137, vcc, 0, v105, vcc
	global_load_ushort v142, v[136:137], off offset:1024
	v_add_co_u32_e32 v136, vcc, s4, v104
	s_mov_b32 s4, 0xc00f000
	s_nop 0
	v_addc_co_u32_e32 v137, vcc, 0, v105, vcc
	global_load_ushort v141, v[136:137], off offset:2560
	v_add_co_u32_e32 v136, vcc, s4, v104
	s_mov_b32 s4, 0xc010000
	s_nop 0
	v_addc_co_u32_e32 v137, vcc, 0, v105, vcc
	global_load_ushort v140, v[136:137], off offset:2048
	v_add_co_u32_e32 v136, vcc, s4, v104
	s_mov_b32 s4, 0xc011000
	s_nop 0
	v_addc_co_u32_e32 v137, vcc, 0, v105, vcc
	global_load_ushort v139, v[136:137], off offset:1536
	v_add_co_u32_e32 v136, vcc, s4, v104
	s_mov_b32 s4, 0xc015000
	s_nop 0
	v_addc_co_u32_e32 v137, vcc, 0, v105, vcc
	global_load_ushort v138, v[136:137], off offset:1024
	v_add_co_u32_e32 v136, vcc, s4, v104
	s_mov_b32 s4, 0xc016000
	s_nop 0
	v_addc_co_u32_e32 v137, vcc, 0, v105, vcc
	v_add_co_u32_e32 v154, vcc, s4, v104
	s_mov_b32 s4, 0xc017000
	s_nop 0
	v_addc_co_u32_e32 v155, vcc, 0, v105, vcc
	global_load_ushort v137, v[136:137], off offset:2560
	v_mul_f32_e32 v0, v89, v0
	global_load_ushort v136, v[154:155], off offset:2048
	v_add_co_u32_e32 v154, vcc, s4, v104
	s_mov_b32 s4, 0xc018000
	s_nop 0
	v_addc_co_u32_e32 v155, vcc, 0, v105, vcc
	v_add_co_u32_e32 v104, vcc, s4, v104
	v_cvt_pk_bf16_f32 v0, v0, s0
	s_nop 0
	v_addc_co_u32_e32 v105, vcc, 0, v105, vcc
	global_load_ushort v135, v[154:155], off offset:1536
	global_load_ushort v89, v[104:105], off offset:1024
	v_add_f32_e32 v1, v1, v147
	global_store_short v[152:153], v0, off offset:1536
	s_waitcnt vmcnt(15)
	v_lshlrev_b32_e32 v0, 16, v146
	v_mul_f32_e32 v104, 0x3dd2d3e8, v0
	v_fma_f32 v104, -v104, v0, s21
	v_mul_f32_e32 v104, v104, v0
	v_exp_f32_e32 v104, v104
	v_add_f32_e32 v3, v3, v149
	s_mov_b64 s[4:5], 0x1c000
	v_lshl_add_u64 v[90:91], v[90:91], 0, s[4:5]
	v_add_f32_e32 v104, 1.0, v104
	v_rcp_f32_e32 v104, v104
	s_nop 0
	v_mul_f32_e32 v0, v104, v0
	v_mul_f32_e32 v0, v0, v1
	v_cvt_pk_bf16_f32 v0, v0, s0
	global_store_short v[152:153], v0, off offset:3584
	s_waitcnt vmcnt(15)
	v_lshlrev_b32_e32 v0, 16, v156
	v_mul_f32_e32 v1, 0x3dd2d3e8, v0
	v_fma_f32 v1, -v1, v0, s21
	v_mul_f32_e32 v1, v1, v0
	v_exp_f32_e32 v1, v1
	s_nop 0
	v_add_f32_e32 v1, 1.0, v1
	v_rcp_f32_e32 v1, v1
	s_nop 0
	v_mul_f32_e32 v0, v1, v0
	v_add_f32_e32 v1, v2, v148
	v_mul_f32_e32 v0, v0, v1
	v_cvt_pk_bf16_f32 v2, v0, s0
	v_add_co_u32_e32 v0, vcc, s23, v150
	s_nop 1
	v_addc_co_u32_e32 v1, vcc, 0, v151, vcc
	global_store_short v[0:1], v2, off offset:1536
	s_waitcnt vmcnt(15)
; __device__ __forceinline__ unsigned short f2bf(float f) { return (unsigned short)(pk2(f, 0.f) & 0xffffu); }
; __device__ __forceinline__ float bf2f(unsigned short h) { return __uint_as_float(((unsigned)h) << 16); }
; __device__ __forceinline__ float gelu_t(float x) { const float t = x * (-2.3022082f + -0.10294324f * x * x); return x * __builtin_amdgcn_rcpf(1.0f + __builtin_amdgcn_exp2f(t)); }
; __device__ __forceinline__ void post_phase(const Params& p, int l, LAS unsigned char* lds, int tid) {
;     ...
;                 for (int pb = 0; pb < 4; ++pb) {
;                     unsigned short uu[16];
; #pragma unroll
;                     for (int e = 0; e < 16; ++e) uu[e] = px[(size_t)(pb * 32 + (e & 3) + 8 * (e >> 2) + 4 * hi) * NIN + 1280 + col];
;                     f32x16 acc;
; #pragma unroll
;                     for (int e = 0; e < 16; ++e) acc[e] = 0.f;
; #pragma unroll
;                     for (int s = 0; s < 8; ++s) {
;                         const bf16x8 a = *(const bf16x8*)(wsb + (size_t)(pb * 32 + r32) * 128 + 16 * s + 8 * hi);
;                         acc = __builtin_amdgcn_mfma_f32_32x32x16_bf16(a, bfr[s], acc, 0, 0, 0);
;                     }
; #pragma unroll
;                     for (int e = 0; e < 16; ++e) {
;                         const int pp = pb * 32 + (e & 3) + 8 * (e >> 2) + 4 * hi;
;                         MIX[(size_t)(R0 + pp) * KOUT + 768 + col] = f2bf(gelu_t(bf2f(uu[e])) * (acc[e] + bs[pp]));
;                     }
;                 }
;             }
;             __syncthreads();
	v_lshlrev_b32_e32 v2, 16, v157
	v_mul_f32_e32 v104, 0x3dd2d3e8, v2
	v_fma_f32 v104, -v104, v2, s21
	v_mul_f32_e32 v104, v104, v2
	v_exp_f32_e32 v104, v104
	s_nop 0
	v_add_f32_e32 v104, 1.0, v104
	v_rcp_f32_e32 v104, v104
	s_nop 0
	v_mul_f32_e32 v2, v104, v2
	v_mul_f32_e32 v2, v2, v3
	v_cvt_pk_bf16_f32 v2, v2, s0
	global_store_short v[0:1], v2, off offset:3584
	s_waitcnt vmcnt(15)
	v_lshlrev_b32_e32 v0, 16, v158
	v_mul_f32_e32 v1, 0x3dd2d3e8, v0
	v_fma_f32 v1, -v1, v0, s21
	v_mul_f32_e32 v1, v1, v0
	v_exp_f32_e32 v1, v1
	s_nop 0
	v_add_f32_e32 v1, 1.0, v1
	v_rcp_f32_e32 v1, v1
	s_nop 0
	v_mul_f32_e32 v104, v1, v0
	global_load_dwordx4 v[0:3], v[102:103], off offset:32
	s_waitcnt vmcnt(0)
	v_add_f32_e32 v0, v4, v0
	v_mul_f32_e32 v0, v104, v0
	v_lshl_add_u64 v[104:105], s[88:89], 0, v[96:97]
	v_add_co_u32_e32 v146, vcc, s22, v104
	v_cvt_pk_bf16_f32 v0, v0, s0
	s_nop 0
	v_addc_co_u32_e32 v147, vcc, 0, v105, vcc
	global_store_short v[146:147], v0, off offset:1536
	v_lshlrev_b32_e32 v0, 16, v145
	v_mul_f32_e32 v4, 0x3dd2d3e8, v0
	v_fma_f32 v4, -v4, v0, s21
	v_mul_f32_e32 v4, v4, v0
	v_exp_f32_e32 v4, v4
	v_add_f32_e32 v1, v5, v1
	v_add_f32_e32 v3, v7, v3
	v_lshl_add_u64 v[96:97], v[96:97], 0, s[96:97]
	v_add_f32_e32 v4, 1.0, v4
	v_rcp_f32_e32 v4, v4
	s_nop 0
	v_mul_f32_e32 v0, v4, v0
	v_mul_f32_e32 v0, v0, v1
	v_cvt_pk_bf16_f32 v0, v0, s0
	global_store_short v[146:147], v0, off offset:3584
	v_lshlrev_b32_e32 v0, 16, v143
	v_mul_f32_e32 v1, 0x3dd2d3e8, v0
	v_fma_f32 v1, -v1, v0, s21
	v_mul_f32_e32 v1, v1, v0
	v_exp_f32_e32 v1, v1
	s_nop 0
	v_add_f32_e32 v1, 1.0, v1
	v_rcp_f32_e32 v1, v1
	s_nop 0
	v_mul_f32_e32 v0, v1, v0
	v_add_f32_e32 v1, v6, v2
	v_mul_f32_e32 v0, v0, v1
	v_cvt_pk_bf16_f32 v2, v0, s0
	v_add_co_u32_e32 v0, vcc, s23, v104
	s_nop 1
	v_addc_co_u32_e32 v1, vcc, 0, v105, vcc
	global_store_short v[0:1], v2, off offset:1536
	v_lshlrev_b32_e32 v2, 16, v142
	v_mul_f32_e32 v4, 0x3dd2d3e8, v2
	v_fma_f32 v4, -v4, v2, s21
	v_mul_f32_e32 v4, v4, v2
	v_exp_f32_e32 v4, v4
	s_nop 0
	v_add_f32_e32 v4, 1.0, v4
	v_rcp_f32_e32 v4, v4
	s_nop 0
	v_mul_f32_e32 v2, v4, v2
	v_mul_f32_e32 v2, v2, v3
	v_cvt_pk_bf16_f32 v2, v2, s0
	global_store_short v[0:1], v2, off offset:3584
	v_lshlrev_b32_e32 v0, 16, v141
	v_mul_f32_e32 v1, 0x3dd2d3e8, v0
	v_fma_f32 v1, -v1, v0, s21
	v_mul_f32_e32 v1, v1, v0
	v_exp_f32_e32 v1, v1
	s_nop 0
	v_add_f32_e32 v1, 1.0, v1
	v_rcp_f32_e32 v1, v1
	s_nop 0
	v_mul_f32_e32 v4, v1, v0
	global_load_dwordx4 v[0:3], v[102:103], off offset:64
	s_waitcnt vmcnt(0)
	v_add_f32_e32 v0, v8, v0
	v_mul_f32_e32 v0, v4, v0
	v_lshl_add_u64 v[4:5], s[88:89], 0, v[94:95]
	v_add_co_u32_e32 v6, vcc, s22, v4
	v_cvt_pk_bf16_f32 v0, v0, s0
	s_nop 0
	v_addc_co_u32_e32 v7, vcc, 0, v5, vcc
	global_store_short v[6:7], v0, off offset:1536
	v_lshlrev_b32_e32 v0, 16, v140
	v_mul_f32_e32 v8, 0x3dd2d3e8, v0
	v_fma_f32 v8, -v8, v0, s21
	v_mul_f32_e32 v8, v8, v0
	v_exp_f32_e32 v8, v8
	v_add_f32_e32 v1, v9, v1
	v_add_f32_e32 v3, v11, v3
	v_lshl_add_u64 v[94:95], v[94:95], 0, s[96:97]
	v_add_f32_e32 v8, 1.0, v8
	v_rcp_f32_e32 v8, v8
	s_nop 0
	v_mul_f32_e32 v0, v8, v0
	v_mul_f32_e32 v0, v0, v1
	v_cvt_pk_bf16_f32 v0, v0, s0
	global_store_short v[6:7], v0, off offset:3584
	v_lshlrev_b32_e32 v0, 16, v139
	v_mul_f32_e32 v1, 0x3dd2d3e8, v0
	v_fma_f32 v1, -v1, v0, s21
	v_mul_f32_e32 v1, v1, v0
	v_exp_f32_e32 v1, v1
	s_nop 0
	v_add_f32_e32 v1, 1.0, v1
	v_rcp_f32_e32 v1, v1
	s_nop 0
	v_mul_f32_e32 v0, v1, v0
	v_add_f32_e32 v1, v10, v2
	v_mul_f32_e32 v0, v0, v1
	v_cvt_pk_bf16_f32 v2, v0, s0
	v_add_co_u32_e32 v0, vcc, s23, v4
	s_nop 1
	v_addc_co_u32_e32 v1, vcc, 0, v5, vcc
	global_store_short v[0:1], v2, off offset:1536
	v_lshlrev_b32_e32 v2, 16, v138
	v_mul_f32_e32 v4, 0x3dd2d3e8, v2
	v_fma_f32 v4, -v4, v2, s21
	v_mul_f32_e32 v4, v4, v2
	v_exp_f32_e32 v4, v4
	s_nop 0
	v_add_f32_e32 v4, 1.0, v4
	v_rcp_f32_e32 v4, v4
	s_nop 0
	v_mul_f32_e32 v2, v4, v2
	v_mul_f32_e32 v2, v2, v3
	v_cvt_pk_bf16_f32 v2, v2, s0
	global_store_short v[0:1], v2, off offset:3584
	v_lshlrev_b32_e32 v0, 16, v137
	v_mul_f32_e32 v1, 0x3dd2d3e8, v0
	v_fma_f32 v1, -v1, v0, s21
	v_mul_f32_e32 v1, v1, v0
	v_exp_f32_e32 v1, v1
	s_nop 0
	v_add_f32_e32 v1, 1.0, v1
	v_rcp_f32_e32 v1, v1
	s_nop 0
	v_mul_f32_e32 v4, v1, v0
	global_load_dwordx4 v[0:3], v[102:103], off offset:96
	s_waitcnt vmcnt(0)
	v_add_f32_e32 v0, v12, v0
	v_mul_f32_e32 v0, v4, v0
	v_lshl_add_u64 v[4:5], s[88:89], 0, v[92:93]
	v_add_co_u32_e32 v6, vcc, s22, v4
	v_cvt_pk_bf16_f32 v0, v0, s0
	s_nop 0
	v_addc_co_u32_e32 v7, vcc, 0, v5, vcc
	global_store_short v[6:7], v0, off offset:1536
	v_lshlrev_b32_e32 v0, 16, v136
	v_mul_f32_e32 v8, 0x3dd2d3e8, v0
	v_fma_f32 v8, -v8, v0, s21
	v_mul_f32_e32 v8, v8, v0
	v_exp_f32_e32 v8, v8
	v_add_f32_e32 v1, v13, v1
	v_add_f32_e32 v3, v15, v3
	v_lshl_add_u64 v[92:93], v[92:93], 0, s[96:97]
	v_add_f32_e32 v8, 1.0, v8
	v_rcp_f32_e32 v8, v8
	s_nop 0
	v_mul_f32_e32 v0, v8, v0
	v_mul_f32_e32 v0, v0, v1
	v_cvt_pk_bf16_f32 v0, v0, s0
	global_store_short v[6:7], v0, off offset:3584
	v_lshlrev_b32_e32 v0, 16, v135
	v_mul_f32_e32 v1, 0x3dd2d3e8, v0
	v_fma_f32 v1, -v1, v0, s21
	v_mul_f32_e32 v1, v1, v0
	v_exp_f32_e32 v1, v1
	s_nop 0
	v_add_f32_e32 v1, 1.0, v1
	v_rcp_f32_e32 v1, v1
	s_nop 0
	v_mul_f32_e32 v0, v1, v0
	v_add_f32_e32 v1, v14, v2
	v_mul_f32_e32 v0, v0, v1
	v_cvt_pk_bf16_f32 v2, v0, s0
	v_add_co_u32_e32 v0, vcc, s23, v4
	s_nop 1
	v_addc_co_u32_e32 v1, vcc, 0, v5, vcc
	global_store_short v[0:1], v2, off offset:1536
	v_lshlrev_b32_e32 v2, 16, v89
	v_mul_f32_e32 v4, 0x3dd2d3e8, v2
	v_fma_f32 v4, -v4, v2, s21
	v_mul_f32_e32 v4, v4, v2
	v_exp_f32_e32 v4, v4
	s_nop 0
	v_add_f32_e32 v4, 1.0, v4
	v_rcp_f32_e32 v4, v4
	s_nop 0
	v_mul_f32_e32 v2, v4, v2
	v_mul_f32_e32 v2, v2, v3
	v_cvt_pk_bf16_f32 v2, v2, s0
	s_add_u32 s0, s0, 0x80
	s_addc_u32 s1, s1, 0
	s_cmpk_eq_i32 s0, 0x200
	global_store_short v[0:1], v2, off offset:3584
	s_cbranch_scc0 .LBB0_358
	v_readlane_b32 s42, v253, 24
	s_mov_b64 s[0:1], 0
	v_readlane_b32 s43, v253, 25
	s_barrier
